# v62 with the whole kernel shifted by 32 bytes: code placement
# baseline (speedup 1.0000x reference)
_Z4mega6Params:
	s_nop 0
	s_nop 0
	s_nop 0
	s_nop 0
	s_nop 0
	s_nop 0
	s_nop 0
	s_nop 0
	s_mov_b64 s[96:97], s[0:1]
	s_load_dword s70, s[96:97], 0x100
	s_load_dwordx2 s[30:31], s[96:97], 0xa8
	s_add_u32 s0, s96, 0x100
	s_addc_u32 s1, s97, 0
	v_and_b32_e32 v1, 0x3ff, v0
	v_writelane_b32 v251, s0, 0
	s_mov_b32 s67, s2
	v_readfirstlane_b32 s2, v1
	v_writelane_b32 v251, s1, 1
	v_cmp_gt_u32_e32 vcc, 4, v1
	s_and_saveexec_b64 s[0:1], vcc
	v_lshl_add_u32 v2, v1, 2, 0
	v_add_u32_e32 v2, 0x23ff0, v2
	v_mov_b32_e32 v3, 0
	ds_write_b32 v2, v3
	s_or_b64 exec, exec, s[0:1]
	s_load_dwordx2 s[48:49], s[96:97], 0xf8
	s_waitcnt lgkmcnt(0)
	s_barrier
	s_add_u32 s12, s30, 0x2d608000
	s_getreg_b32 s0, hwreg(HW_REG_XCC_ID, 0, 4)
	s_addc_u32 s13, s31, 0
	s_and_b32 s36, s0, 15
	v_cmp_eq_u32_e64 s[4:5], 0, v1
	s_mov_b64 s[0:1], exec
	s_nop 0
	v_writelane_b32 v251, s4, 2
	s_nop 1
	v_writelane_b32 v251, s5, 3
	s_and_b64 s[4:5], s[0:1], s[4:5]
	s_mov_b64 exec, s[4:5]
	s_cbranch_execz .LBB0_5
	s_mov_b64 s[4:5], exec
	v_mbcnt_lo_u32_b32 v2, s4, 0
	v_mbcnt_hi_u32_b32 v2, s5, v2
	v_cmp_eq_u32_e32 vcc, 0, v2
	s_and_b64 s[6:7], exec, vcc
	s_mov_b64 exec, s[6:7]
	s_cbranch_execz .LBB0_5
	s_lshl_b32 s3, s36, 8
	s_bcnt1_i32_b64 s4, s[4:5]
	v_mov_b32_e32 v2, s3
	v_mov_b32_e32 v3, s4
	global_atomic_add v2, v3, s[12:13] offset:1024
